# e48: e44 with the out_proj stage-0 panel counter bumped at row-block 5 instead of 6 (complete one row-block earlier when wave 0 checks it)
# speedup vs baseline: 1.0020x; 1.0020x over previous
; __device__ __forceinline__ f32x4 ld_nt(const float* p) { return __builtin_nontemporal_load((const f32x4*)p); }
; __device__ __forceinline__ u32x4 pack8h(const f32x4 v0, const f32x4 v1) { u32x4 w; w.x = pk_h16(v0[0], v0[1]); w.y = pk_h16(v0[2], v0[3]); w.z = pk_h16(v1[0], v1[1]); w.w = pk_h16(v1[2], v1[3]); return w; }
;     __device__ __forceinline__ void operator()(AccRef acc, const Unit& u, int wr, int wc, int fr, int fq) const {
;     ...
;             for (int mp = 0; mp < 2; ++mp) { f32x4 xv[2][2][2];
; #pragma unroll
;                 for (int mm = 0; mm < 2; ++mm)
; #pragma unroll
;                     for (int bj = 0; bj < 2; ++bj)
; #pragma unroll
;                         for (int n = 0; n < 2; ++n) xv[mm][bj][n] = ld_nt(x + (size_t)(row0 + ai * HALF + (mp * 2 + mm) * 16) * D + col0 + bj * HALF + n * 4);
;                 __builtin_amdgcn_sched_barrier(0);
; #pragma unroll
;                 for (int mm = 0; mm < 2; ++mm) { const int m = mp * 2 + mm; const int row = row0 + ai * HALF + m * 16; const size_t o = (size_t)row * D + col0; float ss = 0.f;
; #pragma unroll
;                     for (int bj = 0; bj < 2; ++bj) { const f32x4 r0 = xv[mm][bj][0] + gv[bj][0] * acc[ai][bj][m][0], r1 = xv[mm][bj][1] + gv[bj][1] * acc[ai][bj][m][1];
;                         *(u32x4*)(xo + o + bj * HALF) = pack8h(r0, r1);
;                         ss += ((r0[0] * r0[0] + r0[1] * r0[1]) + (r0[2] * r0[2] + r0[3] * r0[3])) + ((r1[0] * r1[0] + r1[1] * r1[1]) + (r1[2] * r1[2] + r1[3] * r1[3])); }
.LBB0_1154:
	v_lshl_add_u32 v172, s58, 8, v178
	v_lshrrev_b32_e32 v170, 4, v184
	v_and_b32_e32 v171, 0x60, v180
	v_lshl_or_b32 v170, v170, 2, v171
	v_lshl_or_b32 v170, s22, 8, v170
	v_readlane_b32 s80, v254, 2
	v_readlane_b32 s81, v254, 3
	v_lshlrev_b32_e32 v173, 13, v172
	v_lshlrev_b32_e32 v187, 7, v172
	v_lshlrev_b32_e32 v171, 2, v170
	v_lshl_add_u32 v173, v170, 2, v173
	s_lshl_b32 s18, s22, 2
	s_add_u32 s18, s18, s72
	s_lshl_b32 s18, s18, 2
	s_add_u32 s88, s26, s18
	s_addc_u32 s89, s27, 0
	v_xor_b32_e32 v186, 16, v184
	v_xor_b32_e32 v185, 32, v184
	v_lshrrev_b32_e32 v174, 4, v184
	v_lshlrev_b32_e32 v186, 2, v186
	v_lshlrev_b32_e32 v185, 2, v185
	v_lshl_add_u32 v174, v174, 4, v187
	s_mov_b32 s94, 0x3a000000
	s_mov_b32 s95, 0x358637bd
	s_mov_b64 s[82:83], s[48:49]
	s_lshr_b32 s59, s65, 10
	global_load_dwordx4 v[144:147], v171, s[46:47]
	global_load_dwordx4 v[148:151], v171, s[46:47] offset:64
	global_load_dwordx4 v[152:155], v171, s[46:47] offset:512
	global_load_dwordx4 v[156:159], v171, s[46:47] offset:576
	s_add_u32 s84, s80, 0x20000
	s_addc_u32 s85, s81, 0
	global_load_dwordx4 v[188:191], v173, s[84:85] nt
	global_load_dwordx4 v[192:195], v173, s[84:85] offset:64 nt
	global_load_dwordx4 v[196:199], v173, s[84:85] offset:512 nt
	global_load_dwordx4 v[200:203], v173, s[84:85] offset:576 nt
	s_add_u32 s84, s80, 0x40000
	s_addc_u32 s85, s81, 0
	global_load_dwordx4 v[104:107], v173, s[84:85] nt
	global_load_dwordx4 v[108:111], v173, s[84:85] offset:64 nt
	global_load_dwordx4 v[112:115], v173, s[84:85] offset:512 nt
	global_load_dwordx4 v[120:123], v173, s[84:85] offset:576 nt
	s_waitcnt vmcnt(12)
	v_pk_fma_f32 v[140:141], v[140:141], v[218:219], v[234:235]
	v_pk_fma_f32 v[142:143], v[142:143], v[220:221], v[236:237]
	v_pk_fma_f32 v[136:137], v[136:137], v[222:223], v[238:239]
	v_pk_fma_f32 v[138:139], v[138:139], v[224:225], v[240:241]
	v_pk_fma_f32 v[132:133], v[132:133], v[226:227], v[242:243]
	v_pk_fma_f32 v[134:135], v[134:135], v[228:229], v[244:245]
	v_pk_fma_f32 v[128:129], v[128:129], v[230:231], v[246:247]
	v_pk_fma_f32 v[130:131], v[130:131], v[232:233], v[248:249]
	s_add_u32 s84, s80, 0x60000
	s_addc_u32 s85, s81, 0
	global_load_dwordx4 v[234:237], v173, s[84:85] nt
	global_load_dwordx4 v[238:241], v173, s[84:85] offset:64 nt
	global_load_dwordx4 v[242:245], v173, s[84:85] offset:512 nt
	global_load_dwordx4 v[246:249], v173, s[84:85] offset:576 nt
	v_pk_mul_f32 v[176:177], v[140:141], v[140:141]
	v_pk_fma_f32 v[176:177], v[142:143], v[142:143], v[176:177]
	v_pk_fma_f32 v[176:177], v[136:137], v[136:137], v[176:177]
	v_pk_fma_f32 v[176:177], v[138:139], v[138:139], v[176:177]
	v_pk_fma_f32 v[176:177], v[132:133], v[132:133], v[176:177]
	v_pk_fma_f32 v[176:177], v[134:135], v[134:135], v[176:177]
	v_pk_fma_f32 v[176:177], v[128:129], v[128:129], v[176:177]
	v_pk_fma_f32 v[176:177], v[130:131], v[130:131], v[176:177]
	v_add_f32_e32 v204, v176, v177
	s_waitcnt vmcnt(8)
	v_pk_fma_f32 v[124:125], v[124:125], v[218:219], v[188:189]
	v_pk_fma_f32 v[126:127], v[126:127], v[220:221], v[190:191]
	v_pk_fma_f32 v[116:117], v[116:117], v[222:223], v[192:193]
	v_pk_fma_f32 v[118:119], v[118:119], v[224:225], v[194:195]
	v_pk_fma_f32 v[100:101], v[100:101], v[226:227], v[196:197]
	v_pk_fma_f32 v[102:103], v[102:103], v[228:229], v[198:199]
	v_pk_fma_f32 v[96:97], v[96:97], v[230:231], v[200:201]
	v_pk_fma_f32 v[98:99], v[98:99], v[232:233], v[202:203]
	s_add_u32 s84, s80, 0x100000
	s_addc_u32 s85, s81, 0
	global_load_dwordx4 v[188:191], v173, s[84:85] nt
	global_load_dwordx4 v[192:195], v173, s[84:85] offset:64 nt
	global_load_dwordx4 v[196:199], v173, s[84:85] offset:512 nt
	global_load_dwordx4 v[200:203], v173, s[84:85] offset:576 nt
	v_pk_mul_f32 v[176:177], v[124:125], v[124:125]
	v_pk_fma_f32 v[176:177], v[126:127], v[126:127], v[176:177]
	v_pk_fma_f32 v[176:177], v[116:117], v[116:117], v[176:177]
	v_pk_fma_f32 v[176:177], v[118:119], v[118:119], v[176:177]
	v_pk_fma_f32 v[176:177], v[100:101], v[100:101], v[176:177]
	v_pk_fma_f32 v[176:177], v[102:103], v[102:103], v[176:177]
	v_pk_fma_f32 v[176:177], v[96:97], v[96:97], v[176:177]
	v_pk_fma_f32 v[176:177], v[98:99], v[98:99], v[176:177]
	v_add_f32_e32 v205, v176, v177
	s_waitcnt vmcnt(8)
	v_pk_fma_f32 v[92:93], v[92:93], v[218:219], v[104:105]
	v_pk_fma_f32 v[94:95], v[94:95], v[220:221], v[106:107]
	v_pk_fma_f32 v[88:89], v[88:89], v[222:223], v[108:109]
	v_pk_fma_f32 v[90:91], v[90:91], v[224:225], v[110:111]
	v_pk_fma_f32 v[84:85], v[84:85], v[226:227], v[112:113]
	v_pk_fma_f32 v[86:87], v[86:87], v[228:229], v[114:115]
	v_pk_fma_f32 v[80:81], v[80:81], v[230:231], v[120:121]
	v_pk_fma_f32 v[82:83], v[82:83], v[232:233], v[122:123]
	s_add_u32 s84, s80, 0x120000
	s_addc_u32 s85, s81, 0
	global_load_dwordx4 v[104:107], v173, s[84:85] nt
	global_load_dwordx4 v[108:111], v173, s[84:85] offset:64 nt
	global_load_dwordx4 v[112:115], v173, s[84:85] offset:512 nt
	global_load_dwordx4 v[120:123], v173, s[84:85] offset:576 nt
	v_pk_mul_f32 v[176:177], v[92:93], v[92:93]
	v_pk_fma_f32 v[176:177], v[94:95], v[94:95], v[176:177]
	v_pk_fma_f32 v[176:177], v[88:89], v[88:89], v[176:177]
	v_pk_fma_f32 v[176:177], v[90:91], v[90:91], v[176:177]
	v_pk_fma_f32 v[176:177], v[84:85], v[84:85], v[176:177]
	v_pk_fma_f32 v[176:177], v[86:87], v[86:87], v[176:177]
	v_pk_fma_f32 v[176:177], v[80:81], v[80:81], v[176:177]
	v_pk_fma_f32 v[176:177], v[82:83], v[82:83], v[176:177]
	v_add_f32_e32 v206, v176, v177
	s_waitcnt vmcnt(8)
; __device__ __forceinline__ u32x4 pack8h(const f32x4 v0, const f32x4 v1) { u32x4 w; w.x = pk_h16(v0[0], v0[1]); w.y = pk_h16(v0[2], v0[3]); w.z = pk_h16(v1[0], v1[1]); w.w = pk_h16(v1[2], v1[3]); return w; }
;     __device__ __forceinline__ void operator()(AccRef acc, const Unit& u, int wr, int wc, int fr, int fq) const {
;     ...
;                 for (int mm = 0; mm < 2; ++mm) { const int m = mp * 2 + mm; const int row = row0 + ai * HALF + m * 16; const size_t o = (size_t)row * D + col0; float ss = 0.f;
; #pragma unroll
;                     for (int bj = 0; bj < 2; ++bj) { const f32x4 r0 = xv[mm][bj][0] + gv[bj][0] * acc[ai][bj][m][0], r1 = xv[mm][bj][1] + gv[bj][1] * acc[ai][bj][m][1];
;                         *(u32x4*)(xo + o + bj * HALF) = pack8h(r0, r1);
;                         ss += ((r0[0] * r0[0] + r0[1] * r0[1]) + (r0[2] * r0[2] + r0[3] * r0[3])) + ((r1[0] * r1[0] + r1[1] * r1[1]) + (r1[2] * r1[2] + r1[3] * r1[3])); }
;                     ss += __shfl_xor(ss, 16); ss += __shfl_xor(ss, 32);
;                     if (fq == 0) rowss[(size_t)row * 32 + u.pn * 4 + wc] = ss; } }
	v_pk_fma_f32 v[76:77], v[76:77], v[218:219], v[234:235]
	v_pk_fma_f32 v[78:79], v[78:79], v[220:221], v[236:237]
	v_pk_fma_f32 v[72:73], v[72:73], v[222:223], v[238:239]
	v_pk_fma_f32 v[74:75], v[74:75], v[224:225], v[240:241]
	v_pk_fma_f32 v[68:69], v[68:69], v[226:227], v[242:243]
	v_pk_fma_f32 v[70:71], v[70:71], v[228:229], v[244:245]
	v_pk_fma_f32 v[64:65], v[64:65], v[230:231], v[246:247]
	v_pk_fma_f32 v[66:67], v[66:67], v[232:233], v[248:249]
	s_add_u32 s84, s80, 0x140000
	s_addc_u32 s85, s81, 0
	global_load_dwordx4 v[234:237], v173, s[84:85] nt
	global_load_dwordx4 v[238:241], v173, s[84:85] offset:64 nt
	global_load_dwordx4 v[242:245], v173, s[84:85] offset:512 nt
	global_load_dwordx4 v[246:249], v173, s[84:85] offset:576 nt
	v_pk_mul_f32 v[176:177], v[76:77], v[76:77]
	v_pk_fma_f32 v[176:177], v[78:79], v[78:79], v[176:177]
	v_pk_fma_f32 v[176:177], v[72:73], v[72:73], v[176:177]
	v_pk_fma_f32 v[176:177], v[74:75], v[74:75], v[176:177]
	v_pk_fma_f32 v[176:177], v[68:69], v[68:69], v[176:177]
	v_pk_fma_f32 v[176:177], v[70:71], v[70:71], v[176:177]
	v_pk_fma_f32 v[176:177], v[64:65], v[64:65], v[176:177]
	v_pk_fma_f32 v[176:177], v[66:67], v[66:67], v[176:177]
	v_add_f32_e32 v207, v176, v177
	ds_bpermute_b32 v214, v186, v204
	ds_bpermute_b32 v215, v186, v205
	ds_bpermute_b32 v216, v186, v206
	ds_bpermute_b32 v217, v186, v207
	s_waitcnt lgkmcnt(0)
	v_pk_add_f32 v[204:205], v[204:205], v[214:215]
	v_pk_add_f32 v[206:207], v[206:207], v[216:217]
	ds_bpermute_b32 v214, v185, v204
	ds_bpermute_b32 v215, v185, v205
	ds_bpermute_b32 v216, v185, v206
	ds_bpermute_b32 v217, v185, v207
	s_waitcnt lgkmcnt(0)
	v_pk_add_f32 v[204:205], v[204:205], v[214:215]
	v_pk_add_f32 v[206:207], v[206:207], v[216:217]
	s_and_saveexec_b64 s[20:21], s[2:3]
	s_mov_b64 s[90:91], s[88:89]
	global_store_dword v187, v204, s[90:91] sc0 sc1
	s_add_u32 s90, s88, 0x800
	s_addc_u32 s91, s89, 0
	global_store_dword v187, v205, s[90:91] sc0 sc1
	s_add_u32 s90, s88, 0x1000
	s_addc_u32 s91, s89, 0
	global_store_dword v187, v206, s[90:91] sc0 sc1
	s_add_u32 s90, s88, 0x1800
	s_addc_u32 s91, s89, 0
	global_store_dword v187, v207, s[90:91] sc0 sc1
	s_or_b64 exec, exec, s[20:21]
	s_waitcnt vmcnt(12)
	v_pk_fma_f32 v[60:61], v[60:61], v[218:219], v[188:189]
	v_pk_fma_f32 v[62:63], v[62:63], v[220:221], v[190:191]
	v_pk_fma_f32 v[56:57], v[56:57], v[222:223], v[192:193]
	v_pk_fma_f32 v[58:59], v[58:59], v[224:225], v[194:195]
	v_pk_fma_f32 v[52:53], v[52:53], v[226:227], v[196:197]
	v_pk_fma_f32 v[54:55], v[54:55], v[228:229], v[198:199]
	v_pk_fma_f32 v[48:49], v[48:49], v[230:231], v[200:201]
	v_pk_fma_f32 v[50:51], v[50:51], v[232:233], v[202:203]
	s_add_u32 s84, s80, 0x160000
	s_addc_u32 s85, s81, 0
	global_load_dwordx4 v[188:191], v173, s[84:85] nt
	global_load_dwordx4 v[192:195], v173, s[84:85] offset:64 nt
	global_load_dwordx4 v[196:199], v173, s[84:85] offset:512 nt
	global_load_dwordx4 v[200:203], v173, s[84:85] offset:576 nt
	v_pk_mul_f32 v[176:177], v[60:61], v[60:61]
	v_pk_fma_f32 v[176:177], v[62:63], v[62:63], v[176:177]
	v_pk_fma_f32 v[176:177], v[56:57], v[56:57], v[176:177]
	v_pk_fma_f32 v[176:177], v[58:59], v[58:59], v[176:177]
	v_pk_fma_f32 v[176:177], v[52:53], v[52:53], v[176:177]
	v_pk_fma_f32 v[176:177], v[54:55], v[54:55], v[176:177]
	v_pk_fma_f32 v[176:177], v[48:49], v[48:49], v[176:177]
	v_pk_fma_f32 v[176:177], v[50:51], v[50:51], v[176:177]
	v_add_f32_e32 v208, v176, v177
	s_waitcnt vmcnt(4)
	v_pk_fma_f32 v[44:45], v[44:45], v[218:219], v[104:105]
	v_pk_fma_f32 v[46:47], v[46:47], v[220:221], v[106:107]
	v_pk_fma_f32 v[40:41], v[40:41], v[222:223], v[108:109]
	v_pk_fma_f32 v[42:43], v[42:43], v[224:225], v[110:111]
	v_pk_fma_f32 v[36:37], v[36:37], v[226:227], v[112:113]
	v_pk_fma_f32 v[38:39], v[38:39], v[228:229], v[114:115]
	v_pk_fma_f32 v[32:33], v[32:33], v[230:231], v[120:121]
	v_pk_fma_f32 v[34:35], v[34:35], v[232:233], v[122:123]
	v_pk_mul_f32 v[176:177], v[44:45], v[44:45]
	v_pk_fma_f32 v[176:177], v[46:47], v[46:47], v[176:177]
	v_pk_fma_f32 v[176:177], v[40:41], v[40:41], v[176:177]
	v_pk_fma_f32 v[176:177], v[42:43], v[42:43], v[176:177]
	v_pk_fma_f32 v[176:177], v[36:37], v[36:37], v[176:177]
	v_pk_fma_f32 v[176:177], v[38:39], v[38:39], v[176:177]
	v_pk_fma_f32 v[176:177], v[32:33], v[32:33], v[176:177]
	v_pk_fma_f32 v[176:177], v[34:35], v[34:35], v[176:177]
	v_add_f32_e32 v209, v176, v177
	s_barrier
	s_cmp_lg_u32 s59, 0
	s_cbranch_scc1 .Lepi_a1
	s_lshl_b32 s18, s58, 6
	s_add_u32 s18, s18, 0xc000
	s_mov_b64 exec, 1
	v_mov_b32_e32 v175, s18
	v_mov_b32_e32 v255, 1
	global_atomic_add v175, v255, s[50:51]
	s_mov_b64 exec, -1
.Lepi_a1:
	v_pk_fma_f32 v[28:29], v[28:29], v[218:219], v[234:235]
	v_pk_fma_f32 v[30:31], v[30:31], v[220:221], v[236:237]
	v_pk_fma_f32 v[24:25], v[24:25], v[222:223], v[238:239]
	v_pk_fma_f32 v[26:27], v[26:27], v[224:225], v[240:241]
	v_pk_fma_f32 v[20:21], v[20:21], v[226:227], v[242:243]
	v_pk_fma_f32 v[22:23], v[22:23], v[228:229], v[244:245]
	v_pk_fma_f32 v[16:17], v[16:17], v[230:231], v[246:247]
	v_pk_fma_f32 v[18:19], v[18:19], v[232:233], v[248:249]
	v_pk_mul_f32 v[176:177], v[28:29], v[28:29]
	v_pk_fma_f32 v[176:177], v[30:31], v[30:31], v[176:177]
	v_pk_fma_f32 v[176:177], v[24:25], v[24:25], v[176:177]
	v_pk_fma_f32 v[176:177], v[26:27], v[26:27], v[176:177]
	v_pk_fma_f32 v[176:177], v[20:21], v[20:21], v[176:177]
	v_pk_fma_f32 v[176:177], v[22:23], v[22:23], v[176:177]
	v_pk_fma_f32 v[176:177], v[16:17], v[16:17], v[176:177]
	v_pk_fma_f32 v[176:177], v[18:19], v[18:19], v[176:177]
	v_add_f32_e32 v210, v176, v177
	s_waitcnt vmcnt(0)
	v_pk_fma_f32 v[12:13], v[12:13], v[218:219], v[188:189]
	v_pk_fma_f32 v[14:15], v[14:15], v[220:221], v[190:191]
	v_pk_fma_f32 v[8:9], v[8:9], v[222:223], v[192:193]
	v_pk_fma_f32 v[10:11], v[10:11], v[224:225], v[194:195]
	v_pk_fma_f32 v[4:5], v[4:5], v[226:227], v[196:197]
	v_pk_fma_f32 v[6:7], v[6:7], v[228:229], v[198:199]
	v_pk_fma_f32 v[0:1], v[0:1], v[230:231], v[200:201]
	v_pk_fma_f32 v[2:3], v[2:3], v[232:233], v[202:203]
	v_pk_mul_f32 v[176:177], v[12:13], v[12:13]
	v_pk_fma_f32 v[176:177], v[14:15], v[14:15], v[176:177]
	v_pk_fma_f32 v[176:177], v[8:9], v[8:9], v[176:177]
	v_pk_fma_f32 v[176:177], v[10:11], v[10:11], v[176:177]
	v_pk_fma_f32 v[176:177], v[4:5], v[4:5], v[176:177]
	v_pk_fma_f32 v[176:177], v[6:7], v[6:7], v[176:177]
	v_pk_fma_f32 v[176:177], v[0:1], v[0:1], v[176:177]
	v_pk_fma_f32 v[176:177], v[2:3], v[2:3], v[176:177]
	v_add_f32_e32 v211, v176, v177
	s_cmp_lg_u32 s59, 0
	s_cbranch_scc1 .Lepi_b1
	s_waitcnt vmcnt(0)
	s_lshl_b32 s18, s58, 6
	s_add_u32 s18, s18, 0xc000
	s_mov_b64 exec, 1
	v_mov_b32_e32 v175, s18
	s_mov_b32 vcc_lo, 0
